# grid barriers: non-leader workgroups poll the cross-XCD release word directly (skip per-XCD release hop); leader XGEN bump removed
# speedup vs baseline: 1.0284x; 1.0006x over previous
.LBB0_120:
	s_or_b64 exec, exec, s[8:9]
	v_cvt_f32_u32_e32 v5, v3
	s_waitcnt vmcnt(0)
	v_readfirstlane_b32 s6, v4
	v_sub_u32_e32 v4, 0, v3
	v_rcp_iflag_f32_e32 v5, v5
	v_add_u32_e32 v6, s6, v2
	v_mul_f32_e32 v5, 0x4f7ffffe, v5
	v_cvt_u32_f32_e32 v5, v5
	v_mul_lo_u32 v2, v4, v5
	v_mul_hi_u32 v2, v5, v2
	v_add_u32_e32 v2, v5, v2
	v_mul_hi_u32 v2, v6, v2
	v_mul_lo_u32 v4, v2, v3
	v_sub_u32_e32 v4, v6, v4
	v_add_u32_e32 v5, 1, v2
	v_cmp_ge_u32_e32 vcc, v4, v3
	s_nop 1
	v_cndmask_b32_e32 v2, v2, v5, vcc
	v_sub_u32_e32 v5, v4, v3
	v_cndmask_b32_e32 v4, v4, v5, vcc
	v_add_u32_e32 v5, 1, v2
	v_cmp_ge_u32_e32 vcc, v4, v3
	v_add_u32_e32 v4, 1, v6
	s_nop 0
	v_cndmask_b32_e32 v2, v2, v5, vcc
	v_mul_lo_u32 v5, v3, v2
	v_add_u32_e32 v3, v5, v3
	v_cmp_ne_u32_e32 vcc, v4, v3
	s_and_saveexec_b64 s[6:7], vcc
	s_xor_b64 s[6:7], exec, s[6:7]
	s_cbranch_execz .LBB0_134
	s_waitcnt lgkmcnt(0)
	v_mov_b32_e32 v1, 0x4000
	global_load_dword v1, v1, s[80:81] offset:1280 sc1
	s_add_u32 s12, s80, 0x4500
	s_addc_u32 s13, s81, 0
	s_waitcnt vmcnt(0)
	v_cmp_eq_u32_e32 vcc, v1, v2
	s_and_saveexec_b64 s[8:9], vcc
	s_cbranch_execz .LBB0_133
	s_add_u32 s10, s80, 0x1200
	s_addc_u32 s11, s81, 0
	s_mov_b32 s38, 1
	s_mov_b64 s[14:15], 0
	v_mov_b32_e32 v1, 0
	s_branch .LBB0_124

.LBB0_151:
	s_or_b64 exec, exec, s[6:7]
	s_mov_b64 s[6:7], exec
	v_mbcnt_lo_u32_b32 v1, s6, 0
	v_mbcnt_hi_u32_b32 v1, s7, v1
	v_cmp_eq_u32_e32 vcc, 0, v1
	s_waitcnt vmcnt(0)
	s_nop 0
	s_and_saveexec_b64 s[8:9], vcc
	s_cbranch_execz .LBB0_153
	s_bcnt1_i32_b64 s6, s[6:7]
	v_mov_b32_e32 v1, 0x2000
	v_mov_b32_e32 v2, s6
	s_nop 0

.LBB0_335:
	s_or_b64 exec, exec, s[8:9]
	v_cvt_f32_u32_e32 v5, v3
	s_waitcnt vmcnt(0)
	v_readfirstlane_b32 s6, v4
	v_sub_u32_e32 v4, 0, v3
	v_rcp_iflag_f32_e32 v5, v5
	v_add_u32_e32 v6, s6, v2
	v_mul_f32_e32 v5, 0x4f7ffffe, v5
	v_cvt_u32_f32_e32 v5, v5
	v_mul_lo_u32 v2, v4, v5
	v_mul_hi_u32 v2, v5, v2
	v_add_u32_e32 v2, v5, v2
	v_mul_hi_u32 v2, v6, v2
	v_mul_lo_u32 v4, v2, v3
	v_sub_u32_e32 v4, v6, v4
	v_add_u32_e32 v5, 1, v2
	v_cmp_ge_u32_e32 vcc, v4, v3
	s_nop 1
	v_cndmask_b32_e32 v2, v2, v5, vcc
	v_sub_u32_e32 v5, v4, v3
	v_cndmask_b32_e32 v4, v4, v5, vcc
	v_add_u32_e32 v5, 1, v2
	v_cmp_ge_u32_e32 vcc, v4, v3
	v_add_u32_e32 v4, 1, v6
	s_nop 0
	v_cndmask_b32_e32 v2, v2, v5, vcc
	v_mul_lo_u32 v5, v3, v2
	v_add_u32_e32 v3, v5, v3
	v_cmp_ne_u32_e32 vcc, v4, v3
	s_and_saveexec_b64 s[6:7], vcc
	s_xor_b64 s[6:7], exec, s[6:7]
	s_cbranch_execz .LBB0_349
	s_waitcnt lgkmcnt(0)
	v_mov_b32_e32 v1, 0x4000
	global_load_dword v1, v1, s[80:81] offset:1280 sc1
	s_add_u32 s12, s80, 0x4500
	s_addc_u32 s13, s81, 0
	s_waitcnt vmcnt(0)
	v_cmp_eq_u32_e32 vcc, v1, v2
	s_and_saveexec_b64 s[8:9], vcc
	s_cbranch_execz .LBB0_348
	s_add_u32 s10, s80, 0x1200
	s_addc_u32 s11, s81, 0
	s_mov_b32 s38, 1
	s_mov_b64 s[20:21], 0
	v_mov_b32_e32 v1, 0
	s_branch .LBB0_339

.LBB0_456:
	s_or_b64 exec, exec, s[8:9]
	v_cvt_f32_u32_e32 v5, v3
	s_waitcnt vmcnt(0)
	v_readfirstlane_b32 s2, v4
	v_sub_u32_e32 v4, 0, v3
	v_rcp_iflag_f32_e32 v5, v5
	v_add_u32_e32 v6, s2, v2
	v_mul_f32_e32 v5, 0x4f7ffffe, v5
	v_cvt_u32_f32_e32 v5, v5
	v_mul_lo_u32 v2, v4, v5
	v_mul_hi_u32 v2, v5, v2
	v_add_u32_e32 v2, v5, v2
	v_mul_hi_u32 v2, v6, v2
	v_mul_lo_u32 v4, v2, v3
	v_sub_u32_e32 v4, v6, v4
	v_add_u32_e32 v5, 1, v2
	v_cmp_ge_u32_e32 vcc, v4, v3
	s_nop 1
	v_cndmask_b32_e32 v2, v2, v5, vcc
	v_sub_u32_e32 v5, v4, v3
	v_cndmask_b32_e32 v4, v4, v5, vcc
	v_add_u32_e32 v5, 1, v2
	v_cmp_ge_u32_e32 vcc, v4, v3
	v_add_u32_e32 v4, 1, v6
	s_nop 0
	v_cndmask_b32_e32 v2, v2, v5, vcc
	v_mul_lo_u32 v5, v3, v2
	v_add_u32_e32 v3, v5, v3
	v_cmp_ne_u32_e32 vcc, v4, v3
	s_and_saveexec_b64 s[2:3], vcc
	s_xor_b64 s[6:7], exec, s[2:3]
	s_cbranch_execz .LBB0_470
	s_waitcnt lgkmcnt(0)
	v_mov_b32_e32 v1, 0x4000
	global_load_dword v1, v1, s[80:81] offset:1280 sc1
	s_add_u32 s12, s80, 0x4500
	s_addc_u32 s13, s81, 0
	s_waitcnt vmcnt(0)
	v_cmp_eq_u32_e32 vcc, v1, v2
	s_and_saveexec_b64 s[8:9], vcc
	s_cbranch_execz .LBB0_469
	s_add_u32 s10, s80, 0x1200
	s_addc_u32 s11, s81, 0
	s_mov_b32 s2, 1
	s_mov_b64 s[20:21], 0
	v_mov_b32_e32 v1, 0
	s_branch .LBB0_460

.LBB0_487:
	s_or_b64 exec, exec, s[2:3]
	s_mov_b64 s[6:7], exec
	v_mbcnt_lo_u32_b32 v1, s6, 0
	v_mbcnt_hi_u32_b32 v1, s7, v1
	v_cmp_eq_u32_e32 vcc, 0, v1
	s_waitcnt vmcnt(0)
	s_nop 0
	s_and_saveexec_b64 s[2:3], vcc
	s_cbranch_execz .LBB0_489
	s_bcnt1_i32_b64 s6, s[6:7]
	v_mov_b32_e32 v1, 0x2000
	v_mov_b32_e32 v2, s6
	s_nop 0
